# conv Toeplitz loop: wave-uniform skip of the eight MFMAs of an N-tile whose B fragments are entirely out of range
# speedup vs baseline: 1.0116x; 1.0005x over previous
; #define MFMA(a, b, c) __builtin_amdgcn_mfma_f32_32x32x16_bf16((a), (b), (c), 0, 0, 0)
; DI void hy_conv_phase(int wvs, char* smem, bf16_t* X1T, const bf16_t* __restrict__ VT, const float* __restrict__ cw, const float* __restrict__ cb,
;                       const bf16_t* __restrict__ KF, const bf16_t* __restrict__ KB, bool dostore = true) {
;     ...
;     for (int d1 = 8 * w - 63; d1 <= 8 * w + 7; ++d1) {
;       const int s1a = t1a - d1, s1b = s1a + 4;
;       const bool va_ = (s1a >= 0) && (s1a < 64), vb_ = (s1b >= 0) && (s1b < 64);
;       const bf16_t* urow0 = Uimg + ((va_ ? s1a : 0) * 8 + b) * 72 + 8 * hh;
;       const bf16_t* urow1 = Uimg + ((vb_ ? s1b : 0) * 8 + b) * 72 + 8 * hh;
;       const int ybase = 4095 - 64 * d1 - n + 8 * hh;
;       bf16x8 b0[4], b1[4], af0[4], af1[4];
;       __builtin_amdgcn_sched_barrier(0);
; #pragma unroll
;       for (int ks = 0; ks < 4; ++ks) {
;         b0[ks] = ldfrag(urow0 + ks * 16); b1[ks] = ldfrag(urow1 + ks * 16);
;         if (ks < 2) {
;           const unsigned* p0 = (const unsigned*)(Rb + ybase + 16 * ks);
;           const unsigned* p1 = (const unsigned*)(Rb + ybase + 16 * ks - 32);
;           u32x4 a0, a1;
;           a0[0] = p0[0]; a0[1] = p0[1]; a0[2] = p0[2]; a0[3] = p0[3];
;           a1[0] = p1[0]; a1[1] = p1[1]; a1[2] = p1[2]; a1[3] = p1[3];
;           af0[ks] = __builtin_bit_cast(bf16x8, a0); af1[ks] = __builtin_bit_cast(bf16x8, a1);
;         }
;       }
;       af0[2] = carry0; af0[3] = carry1; af1[2] = af0[0]; af1[3] = af0[1];
;       carry0 = af1[0]; carry1 = af1[1];
;       if (!va_) {
; #pragma unroll
;         for (int ks = 0; ks < 4; ++ks) for (int j = 0; j < 8; ++j) b0[ks][j] = 0;
;       }
;       if (!vb_) {
; #pragma unroll
;         for (int ks = 0; ks < 4; ++ks) for (int j = 0; j < 8; ++j) b1[ks][j] = 0;
;       }
;       __builtin_amdgcn_sched_barrier(0);
; #pragma unroll
;       for (int ks = 0; ks < 4; ++ks) {
;         acc00 = MFMA(af0[ks], b0[ks], acc00); acc01 = MFMA(af1[ks], b0[ks], acc01);
;         acc10 = MFMA(af0[ks], b1[ks], acc10); acc11 = MFMA(af1[ks], b1[ks], acc11);
;       }
;       __builtin_amdgcn_sched_barrier(0);
;     }
.Lcv_b0only:
	s_waitcnt lgkmcnt(0)
	v_mfma_f32_32x32x16_bf16 v[32:47], v[84:87], v[112:115], v[32:47]
	v_mfma_f32_32x32x16_bf16 v[48:63], v[76:79], v[112:115], v[48:63]
	v_mfma_f32_32x32x16_bf16 v[32:47], v[80:83], v[96:99], v[32:47]
	v_mfma_f32_32x32x16_bf16 v[48:63], v[72:75], v[96:99], v[48:63]
	v_mfma_f32_32x32x16_bf16 v[32:47], v[68:71], v[100:103], v[32:47]
	v_mfma_f32_32x32x16_bf16 v[48:63], v[84:87], v[100:103], v[48:63]
	v_mfma_f32_32x32x16_bf16 v[32:47], v[64:67], v[88:91], v[32:47]
	v_mfma_f32_32x32x16_bf16 v[48:63], v[80:83], v[88:91], v[48:63]
	s_branch .Lcv_join
.Lcv_b1only:
	s_waitcnt lgkmcnt(0)
	v_mfma_f32_32x32x16_bf16 v[0:15], v[84:87], v[116:119], v[0:15]
	v_mfma_f32_32x32x16_bf16 v[16:31], v[76:79], v[116:119], v[16:31]
	v_mfma_f32_32x32x16_bf16 v[0:15], v[80:83], v[108:111], v[0:15]
	v_mfma_f32_32x32x16_bf16 v[16:31], v[72:75], v[108:111], v[16:31]
	v_mfma_f32_32x32x16_bf16 v[0:15], v[68:71], v[104:107], v[0:15]
	v_mfma_f32_32x32x16_bf16 v[16:31], v[84:87], v[104:107], v[16:31]
	v_mfma_f32_32x32x16_bf16 v[0:15], v[64:67], v[92:95], v[0:15]
	v_mfma_f32_32x32x16_bf16 v[16:31], v[80:83], v[92:95], v[16:31]
	s_branch .Lcv_join
.LBB0_1210:
	s_or_b64 exec, exec, s[24:25]
	s_cmp_eq_u64 s[68:69], exec
	s_cbranch_scc1 .Lcv_b0only
	s_cmp_eq_u64 s[66:67], exec
	s_cbranch_scc1 .Lcv_b1only
	s_waitcnt lgkmcnt(10)
	v_mfma_f32_32x32x16_bf16 v[0:15], v[84:87], v[116:119], v[0:15]
	s_waitcnt lgkmcnt(6)
	v_mfma_f32_32x32x16_bf16 v[16:31], v[76:79], v[116:119], v[16:31]
	v_mfma_f32_32x32x16_bf16 v[32:47], v[84:87], v[112:115], v[32:47]
	v_mfma_f32_32x32x16_bf16 v[48:63], v[76:79], v[112:115], v[48:63]
	v_mfma_f32_32x32x16_bf16 v[0:15], v[80:83], v[108:111], v[0:15]
	s_waitcnt lgkmcnt(4)
	v_mfma_f32_32x32x16_bf16 v[16:31], v[72:75], v[108:111], v[16:31]
	v_mfma_f32_32x32x16_bf16 v[32:47], v[80:83], v[96:99], v[32:47]
	v_mfma_f32_32x32x16_bf16 v[48:63], v[72:75], v[96:99], v[48:63]
	s_waitcnt lgkmcnt(1)
	v_mfma_f32_32x32x16_bf16 v[0:15], v[68:71], v[104:107], v[0:15]
	v_mfma_f32_32x32x16_bf16 v[16:31], v[84:87], v[104:107], v[16:31]
	v_mfma_f32_32x32x16_bf16 v[32:47], v[68:71], v[100:103], v[32:47]
	v_mfma_f32_32x32x16_bf16 v[48:63], v[84:87], v[100:103], v[48:63]
	s_waitcnt lgkmcnt(0)
	v_mfma_f32_32x32x16_bf16 v[0:15], v[64:67], v[92:95], v[0:15]
	v_mfma_f32_32x32x16_bf16 v[16:31], v[80:83], v[92:95], v[16:31]
	v_mfma_f32_32x32x16_bf16 v[32:47], v[64:67], v[88:91], v[32:47]
	v_mfma_f32_32x32x16_bf16 v[48:63], v[80:83], v[88:91], v[48:63]
.Lcv_join:
	v_add_u32_e32 v188, 1, v188
	v_cmp_ge_i32_e64 s[66:67], v188, v139
	v_add_u32_e32 v189, 0xffffff80, v189
	v_add_u32_e32 v187, -8, v187
	v_add_u32_e32 v175, -1, v175
	s_or_b64 s[88:89], s[66:67], s[88:89]
	v_mov_b32_e32 v68, v76
	v_mov_b32_e32 v69, v77
	v_mov_b32_e32 v70, v78
	v_mov_b32_e32 v71, v79
	v_mov_b32_e32 v64, v72
	v_mov_b32_e32 v65, v73
	v_mov_b32_e32 v66, v74
	v_mov_b32_e32 v67, v75
	s_andn2_b64 exec, exec, s[88:89]
	s_cbranch_execz .LBB0_1165
